# speedup vs baseline: 1.0045x; 1.0035x over previous
; #define GAS __attribute__((address_space(1)))
; __device__ __forceinline__ uint2 ldnt_u2(const void* q) { u32x2_t v = __builtin_nontemporal_load((const u32x2_t*)q); return make_uint2(v[0], v[1]); }
; __device__ __forceinline__ void sgu_item(PP p, Ctx cx, int g0, int rb_l, int chunk, int tseq, bool samp, int sb, char* smem) {
;     ...
;     bf16x8 bfr[4][2];
; #pragma unroll
;     for (int kk = 0; kk < 4; ++kk)
; #pragma unroll
;       for (int ni = 0; ni < 2; ++ni)
;         if (kk <= kk_max)
;           bfr[kk][ni] = *(GAS const bf16x8*)(Wsb + ((size_t)(g * 128 + t0 + ni * 16 + fr)) * 128 + kk * 32 + fq * 8);
;     uint2 uv[2][4];
;     float bsv[2];
; #pragma unroll
;     for (int ni = 0; ni < 2; ++ni) {
;       int t = t0 + ni * 16 + fr;
;       bsv[ni] = p->b_s[g * 128 + t];
; #pragma unroll
;       for (int mi = 0; mi < 4; ++mi)
;         uv[ni][mi] = (t < nrows) ? ldnt_u2(Ub + (size_t)(r0 + t) * 1024 + g * 128 + c0 + mi * 16 + fq * 4) : make_uint2(0, 0);
;     }
;     __syncthreads();
; #pragma unroll
;     for (int i = 0; i < 4; ++i) {
;       int e = tid + i * 512;
;       int s = e >> 4, cc = (e & 15) * 8;
;       float vn[8];
;       if (s < nrows) {
;         float lg[8], lb[8];
;         ld8f(p->ln_g + g * 128 + cc, lg);
;         ld8f(p->ln_b + g * 128 + cc, lb);
.LBB0_1331:
	s_load_dwordx4 s[36:39], s[0:1], 0x38
	s_waitcnt lgkmcnt(0)
	v_lshl_add_u64 v[250:251], s[36:37], 0, v[112:113]
	v_lshl_add_u64 v[252:253], s[38:39], 0, v[112:113]
	v_lshl_add_u64 v[250:251], v[250:251], 0, s[26:27]
	v_lshl_add_u64 v[252:253], v[252:253], 0, s[26:27]
	global_load_dwordx4 v[234:237], v[250:251], off
	global_load_dwordx4 v[238:241], v[250:251], off offset:16
	global_load_dwordx4 v[242:245], v[252:253], off
	global_load_dwordx4 v[246:249], v[252:253], off offset:16
	s_and_saveexec_b64 s[24:25], s[4:5]
	s_cbranch_execz .LBB0_1339
	v_mov_b32_e32 v145, v0
	v_lshlrev_b64 v[2:3], 8, v[144:145]
	v_lshl_add_u64 v[2:3], v[96:97], 0, v[2:3]
	global_load_dwordx4 v[48:51], v[2:3], off
	s_or_b64 exec, exec, s[24:25]
	v_add_u32_e32 v2, 16, v144
	s_and_saveexec_b64 s[24:25], s[4:5]
	s_cbranch_execnz .LBB0_1340

; #define GAS __attribute__((address_space(1)))
; __device__ __forceinline__ u16 f2bf(float f) { return (u16)(pack2(f, 0.f) & 0xffffu); }
; __device__ __forceinline__ float bf2f(u16 b) { return __uint_as_float(((uint32_t)b) << 16); }
; __device__ __forceinline__ void sgu_item(PP p, Ctx cx, int g0, int rb_l, int chunk, int tseq, bool samp, int sb, char* smem) {
;     ...
;     for (int i = 0; i < 4; ++i) {
;       int e = tid + i * 512;
;       int s = e >> 4, cc = (e & 15) * 8;
;       float vn[8];
;       if (s < nrows) {
;         float lg[8], lb[8];
;         ld8f(p->ln_g + g * 128 + cc, lg);
;         ld8f(p->ln_b + g * 128 + cc, lb);
;         float mu = stats[s * 2], rstd = stats[s * 2 + 1];
;         unsigned w[4] = {tl[i].x, tl[i].y, tl[i].z, tl[i].w};
; #pragma unroll
;         for (int k = 0; k < 4; ++k) {
;           vn[2 * k] = (bf2f((u16)(w[k] & 0xffff)) - mu) * rstd * lg[2 * k] + lb[2 * k];
;           vn[2 * k + 1] = (bf2f((u16)(w[k] >> 16)) - mu) * rstd * lg[2 * k + 1] + lb[2 * k + 1];
;         }
;         if (samp) {
;           float* o = p->out + O_GV + ((size_t)sb * DSEQ + s) * 1024 + g * 128 + cc;
;           *(GAS float4*)(o) = make_float4(vn[0], vn[1], vn[2], vn[3]);
;           *(GAS float4*)(o + 4) = make_float4(vn[4], vn[5], vn[6], vn[7]);
;         }
;       } else {
; #pragma unroll
;         for (int k = 0; k < 8; ++k) vn[k] = 0.f;
;       }
;       int soff = ((((s >> 3) ^ ((cc >> 3) & 15)) << 3) + (s & 7));
; #pragma unroll
;       for (int k = 0; k < 8; ++k) vT[(cc + k) * LDV + soff] = f2bf(vn[k]);
.LBB0_1363:
	s_or_b64 exec, exec, s[24:25]
	v_cndmask_b32_e64 v1, 0, 1, s[44:45]
	v_mov_b32_e32 v52, 0
	v_cmp_ne_u32_e64 s[24:25], 1, v1
	v_mov_b32_e32 v54, 0
	v_mov_b32_e32 v55, 0
	v_mov_b32_e32 v56, 0
	v_mov_b32_e32 v57, 0
	v_mov_b32_e32 v58, 0
	v_mov_b32_e32 v59, 0
	v_mov_b32_e32 v60, 0
	v_mov_b32_e32 v61, 0
	s_waitcnt lgkmcnt(0)
	s_barrier
	s_and_saveexec_b64 s[28:29], s[12:13]
	s_cbranch_execz .LBB0_1366
	ds_read_b64 v[70:71], v195 offset:32768
	s_and_b64 vcc, exec, s[24:25]
	s_waitcnt lgkmcnt(0)
	s_nop 0
	v_lshlrev_b32_e32 v2, 16, v4
	v_and_b32_e32 v3, 0xffff0000, v4
	v_pk_add_f32 v[2:3], v[2:3], v[70:71] op_sel_hi:[1,0] neg_lo:[0,1] neg_hi:[0,1]
	s_nop 0
	v_pk_mul_f32 v[2:3], v[70:71], v[2:3] op_sel:[1,0]
	s_waitcnt vmcnt(0)
	v_pk_fma_f32 v[54:55], v[234:235], v[2:3], v[242:243]
	v_lshlrev_b32_e32 v2, 16, v5
	v_and_b32_e32 v3, 0xffff0000, v5
	v_pk_add_f32 v[2:3], v[2:3], v[70:71] op_sel_hi:[1,0] neg_lo:[0,1] neg_hi:[0,1]
	s_nop 0
	v_pk_mul_f32 v[2:3], v[70:71], v[2:3] op_sel:[1,0]
	s_nop 0
	v_pk_fma_f32 v[56:57], v[236:237], v[2:3], v[244:245]
	v_lshlrev_b32_e32 v2, 16, v6
	v_and_b32_e32 v3, 0xffff0000, v6
	v_pk_add_f32 v[2:3], v[2:3], v[70:71] op_sel_hi:[1,0] neg_lo:[0,1] neg_hi:[0,1]
	s_nop 0
	v_pk_mul_f32 v[2:3], v[70:71], v[2:3] op_sel:[1,0]
	s_nop 0
	v_pk_fma_f32 v[58:59], v[238:239], v[2:3], v[246:247]
	v_lshlrev_b32_e32 v2, 16, v7
	v_and_b32_e32 v3, 0xffff0000, v7
	v_pk_add_f32 v[2:3], v[2:3], v[70:71] op_sel_hi:[1,0] neg_lo:[0,1] neg_hi:[0,1]
	s_nop 0
	v_pk_mul_f32 v[2:3], v[70:71], v[2:3] op_sel:[1,0]
	s_nop 0
	v_pk_fma_f32 v[60:61], v[240:241], v[2:3], v[248:249]
	s_cbranch_vccnz .LBB0_1366
	s_load_dwordx2 s[30:31], s[0:1], 0xb8
	s_waitcnt lgkmcnt(0)
	v_lshl_add_u64 v[2:3], s[30:31], 0, v[132:133]
	v_lshl_add_u64 v[2:3], v[2:3], 0, s[26:27]
	v_add_co_u32_e32 v2, vcc, 0x307b8000, v2
	s_nop 1
	v_addc_co_u32_e32 v3, vcc, 0, v3, vcc
	global_store_dwordx4 v[2:3], v[54:57], off
	global_store_dwordx4 v[2:3], v[58:61], off offset:16
.LBB0_1366:
	s_or_b64 exec, exec, s[28:29]
	v_cvt_pk_bf16_f32 v1, v54, s0
	ds_write_b16 v95, v1
	v_cvt_pk_bf16_f32 v1, v55, s0
	ds_write_b16 v95, v1 offset:256
	v_cvt_pk_bf16_f32 v1, v56, s0
	ds_write_b16 v95, v1 offset:512
	v_cvt_pk_bf16_f32 v1, v57, s0
	ds_write_b16 v95, v1 offset:768
	v_cvt_pk_bf16_f32 v1, v58, s0
	ds_write_b16 v95, v1 offset:1024
	v_cvt_pk_bf16_f32 v1, v59, s0
	ds_write_b16 v95, v1 offset:1280
	v_cvt_pk_bf16_f32 v1, v60, s0
	ds_write_b16 v95, v1 offset:1536
	v_cvt_pk_bf16_f32 v1, v61, s0
	v_mov_b32_e32 v53, 0
	v_mov_b32_e32 v54, 0
	v_mov_b32_e32 v55, 0
	v_mov_b32_e32 v56, 0
	v_mov_b32_e32 v57, 0
	v_mov_b32_e32 v58, 0
	v_mov_b32_e32 v59, 0
	ds_write_b16 v95, v1 offset:1792
	s_and_saveexec_b64 s[28:29], s[14:15]
	s_cbranch_execz .LBB0_1369
	ds_read_b64 v[68:69], v87 offset:32768
	s_and_b64 vcc, exec, s[24:25]
	s_waitcnt lgkmcnt(0)
	s_nop 0
	v_lshlrev_b32_e32 v2, 16, v8
	v_and_b32_e32 v3, 0xffff0000, v8
	v_pk_add_f32 v[2:3], v[2:3], v[68:69] op_sel_hi:[1,0] neg_lo:[0,1] neg_hi:[0,1]
	s_nop 0
	v_pk_mul_f32 v[2:3], v[68:69], v[2:3] op_sel:[1,0]
	s_waitcnt vmcnt(0)
	v_pk_fma_f32 v[52:53], v[234:235], v[2:3], v[242:243]
	v_lshlrev_b32_e32 v2, 16, v9
	v_and_b32_e32 v3, 0xffff0000, v9
	v_pk_add_f32 v[2:3], v[2:3], v[68:69] op_sel_hi:[1,0] neg_lo:[0,1] neg_hi:[0,1]
	s_nop 0
	v_pk_mul_f32 v[2:3], v[68:69], v[2:3] op_sel:[1,0]
	s_nop 0
	v_pk_fma_f32 v[54:55], v[236:237], v[2:3], v[244:245]
	v_lshlrev_b32_e32 v2, 16, v10
	v_and_b32_e32 v3, 0xffff0000, v10
	v_pk_add_f32 v[2:3], v[2:3], v[68:69] op_sel_hi:[1,0] neg_lo:[0,1] neg_hi:[0,1]
	s_nop 0
	v_pk_mul_f32 v[2:3], v[68:69], v[2:3] op_sel:[1,0]
	s_nop 0
	v_pk_fma_f32 v[56:57], v[238:239], v[2:3], v[246:247]
	v_lshlrev_b32_e32 v2, 16, v11
	v_and_b32_e32 v3, 0xffff0000, v11
	v_pk_add_f32 v[2:3], v[2:3], v[68:69] op_sel_hi:[1,0] neg_lo:[0,1] neg_hi:[0,1]
	s_nop 0
	v_pk_mul_f32 v[2:3], v[68:69], v[2:3] op_sel:[1,0]
	s_nop 0
	v_pk_fma_f32 v[58:59], v[240:241], v[2:3], v[248:249]
	s_cbranch_vccnz .LBB0_1369
	s_load_dwordx2 s[30:31], s[0:1], 0xb8
	s_waitcnt lgkmcnt(0)
	v_lshl_add_u64 v[2:3], s[30:31], 0, v[134:135]
	v_lshl_add_u64 v[2:3], v[2:3], 0, s[26:27]
	v_add_co_u32_e32 v2, vcc, 0x307b8000, v2
	s_nop 1
	v_addc_co_u32_e32 v3, vcc, 0, v3, vcc
	global_store_dwordx4 v[2:3], v[52:55], off
	global_store_dwordx4 v[2:3], v[56:59], off offset:16
; #define GAS __attribute__((address_space(1)))
; __device__ __forceinline__ u16 f2bf(float f) { return (u16)(pack2(f, 0.f) & 0xffffu); }
; __device__ __forceinline__ float bf2f(u16 b) { return __uint_as_float(((uint32_t)b) << 16); }
; __device__ __forceinline__ void sgu_item(PP p, Ctx cx, int g0, int rb_l, int chunk, int tseq, bool samp, int sb, char* smem) {
;     ...
;     for (int i = 0; i < 4; ++i) {
;       int e = tid + i * 512;
;       int s = e >> 4, cc = (e & 15) * 8;
;       float vn[8];
;       if (s < nrows) {
;         float lg[8], lb[8];
;         ld8f(p->ln_g + g * 128 + cc, lg);
;         ld8f(p->ln_b + g * 128 + cc, lb);
;         float mu = stats[s * 2], rstd = stats[s * 2 + 1];
;         unsigned w[4] = {tl[i].x, tl[i].y, tl[i].z, tl[i].w};
; #pragma unroll
;         for (int k = 0; k < 4; ++k) {
;           vn[2 * k] = (bf2f((u16)(w[k] & 0xffff)) - mu) * rstd * lg[2 * k] + lb[2 * k];
;           vn[2 * k + 1] = (bf2f((u16)(w[k] >> 16)) - mu) * rstd * lg[2 * k + 1] + lb[2 * k + 1];
;         }
;         if (samp) {
;           float* o = p->out + O_GV + ((size_t)sb * DSEQ + s) * 1024 + g * 128 + cc;
;           *(GAS float4*)(o) = make_float4(vn[0], vn[1], vn[2], vn[3]);
;           *(GAS float4*)(o + 4) = make_float4(vn[4], vn[5], vn[6], vn[7]);
;         }
;       } else {
; #pragma unroll
;         for (int k = 0; k < 8; ++k) vn[k] = 0.f;
;       }
;       int soff = ((((s >> 3) ^ ((cc >> 3) & 15)) << 3) + (s & 7));
; #pragma unroll
;       for (int k = 0; k < 8; ++k) vT[(cc + k) * LDV + soff] = f2bf(vn[k]);
.LBB0_1369:
	s_or_b64 exec, exec, s[28:29]
	v_cvt_pk_bf16_f32 v1, v52, s0
	ds_write_b16 v227, v1
	v_cvt_pk_bf16_f32 v1, v53, s0
	ds_write_b16 v227, v1 offset:256
	v_cvt_pk_bf16_f32 v1, v54, s0
	ds_write_b16 v227, v1 offset:512
	v_cvt_pk_bf16_f32 v1, v55, s0
	ds_write_b16 v227, v1 offset:768
	v_cvt_pk_bf16_f32 v1, v56, s0
	ds_write_b16 v227, v1 offset:1024
	v_cvt_pk_bf16_f32 v1, v57, s0
	ds_write_b16 v227, v1 offset:1280
	v_cvt_pk_bf16_f32 v1, v58, s0
	ds_write_b16 v227, v1 offset:1536
	v_cvt_pk_bf16_f32 v1, v59, s0
	v_mov_b32_e32 v52, 0
	v_mov_b32_e32 v54, 0
	v_mov_b32_e32 v55, 0
	v_mov_b32_e32 v56, 0
	v_mov_b32_e32 v57, 0
	v_mov_b32_e32 v58, 0
	v_mov_b32_e32 v59, 0
	v_mov_b32_e32 v60, 0
	v_mov_b32_e32 v61, 0
	ds_write_b16 v227, v1 offset:1792
	s_and_saveexec_b64 s[28:29], s[16:17]
	s_cbranch_execz .LBB0_1372
	ds_read_b64 v[70:71], v89 offset:32768
	s_and_b64 vcc, exec, s[24:25]
	s_waitcnt lgkmcnt(0)
	s_nop 0
	v_lshlrev_b32_e32 v2, 16, v12
	v_and_b32_e32 v3, 0xffff0000, v12
	v_pk_add_f32 v[2:3], v[2:3], v[70:71] op_sel_hi:[1,0] neg_lo:[0,1] neg_hi:[0,1]
	s_nop 0
	v_pk_mul_f32 v[2:3], v[70:71], v[2:3] op_sel:[1,0]
	s_waitcnt vmcnt(0)
	v_pk_fma_f32 v[54:55], v[234:235], v[2:3], v[242:243]
	v_lshlrev_b32_e32 v2, 16, v13
	v_and_b32_e32 v3, 0xffff0000, v13
	v_pk_add_f32 v[2:3], v[2:3], v[70:71] op_sel_hi:[1,0] neg_lo:[0,1] neg_hi:[0,1]
	s_nop 0
	v_pk_mul_f32 v[2:3], v[70:71], v[2:3] op_sel:[1,0]
	s_nop 0
	v_pk_fma_f32 v[56:57], v[236:237], v[2:3], v[244:245]
	v_lshlrev_b32_e32 v2, 16, v14
	v_and_b32_e32 v3, 0xffff0000, v14
	v_pk_add_f32 v[2:3], v[2:3], v[70:71] op_sel_hi:[1,0] neg_lo:[0,1] neg_hi:[0,1]
	s_nop 0
	v_pk_mul_f32 v[2:3], v[70:71], v[2:3] op_sel:[1,0]
	s_nop 0
	v_pk_fma_f32 v[58:59], v[238:239], v[2:3], v[246:247]
	v_lshlrev_b32_e32 v2, 16, v15
	v_and_b32_e32 v3, 0xffff0000, v15
	v_pk_add_f32 v[2:3], v[2:3], v[70:71] op_sel_hi:[1,0] neg_lo:[0,1] neg_hi:[0,1]
	s_nop 0
	v_pk_mul_f32 v[2:3], v[70:71], v[2:3] op_sel:[1,0]
	s_nop 0
	v_pk_fma_f32 v[60:61], v[240:241], v[2:3], v[248:249]
	s_cbranch_vccnz .LBB0_1372
	s_load_dwordx2 s[30:31], s[0:1], 0xb8
	s_waitcnt lgkmcnt(0)
	v_lshl_add_u64 v[2:3], s[30:31], 0, v[136:137]
	v_lshl_add_u64 v[2:3], v[2:3], 0, s[26:27]
	v_add_co_u32_e32 v2, vcc, 0x307b8000, v2
	s_nop 1
	v_addc_co_u32_e32 v3, vcc, 0, v3, vcc
	global_store_dwordx4 v[2:3], v[54:57], off
	global_store_dwordx4 v[2:3], v[58:61], off offset:16
.LBB0_1372:
	s_or_b64 exec, exec, s[28:29]
	v_cvt_pk_bf16_f32 v1, v54, s0
	ds_write_b16 v228, v1
	v_cvt_pk_bf16_f32 v1, v55, s0
	ds_write_b16 v228, v1 offset:256
	v_cvt_pk_bf16_f32 v1, v56, s0
	ds_write_b16 v228, v1 offset:512
	v_cvt_pk_bf16_f32 v1, v57, s0
	ds_write_b16 v228, v1 offset:768
	v_cvt_pk_bf16_f32 v1, v58, s0
	ds_write_b16 v228, v1 offset:1024
	v_cvt_pk_bf16_f32 v1, v59, s0
	ds_write_b16 v228, v1 offset:1280
	v_cvt_pk_bf16_f32 v1, v60, s0
	ds_write_b16 v228, v1 offset:1536
	v_cvt_pk_bf16_f32 v1, v61, s0
	v_mov_b32_e32 v53, 0
	v_mov_b32_e32 v54, 0
	v_mov_b32_e32 v55, 0
	v_mov_b32_e32 v56, 0
	v_mov_b32_e32 v57, 0
	v_mov_b32_e32 v58, 0
	v_mov_b32_e32 v59, 0
	ds_write_b16 v228, v1 offset:1792
	s_and_saveexec_b64 s[28:29], s[18:19]
	s_cbranch_execz .LBB0_1375
	ds_read_b64 v[68:69], v91 offset:32768
	s_and_b64 vcc, exec, s[24:25]
	s_waitcnt lgkmcnt(0)
	s_nop 0
	v_lshlrev_b32_e32 v2, 16, v16
	v_and_b32_e32 v3, 0xffff0000, v16
	v_pk_add_f32 v[2:3], v[2:3], v[68:69] op_sel_hi:[1,0] neg_lo:[0,1] neg_hi:[0,1]
	s_nop 0
	v_pk_mul_f32 v[2:3], v[68:69], v[2:3] op_sel:[1,0]
	s_waitcnt vmcnt(0)
	v_pk_fma_f32 v[52:53], v[234:235], v[2:3], v[242:243]
	v_lshlrev_b32_e32 v2, 16, v17
	v_and_b32_e32 v3, 0xffff0000, v17
	v_pk_add_f32 v[2:3], v[2:3], v[68:69] op_sel_hi:[1,0] neg_lo:[0,1] neg_hi:[0,1]
	s_nop 0
	v_pk_mul_f32 v[2:3], v[68:69], v[2:3] op_sel:[1,0]
	s_nop 0
	v_pk_fma_f32 v[54:55], v[236:237], v[2:3], v[244:245]
	v_lshlrev_b32_e32 v2, 16, v18
	v_and_b32_e32 v3, 0xffff0000, v18
	v_pk_add_f32 v[2:3], v[2:3], v[68:69] op_sel_hi:[1,0] neg_lo:[0,1] neg_hi:[0,1]
	s_nop 0
	v_pk_mul_f32 v[2:3], v[68:69], v[2:3] op_sel:[1,0]
	s_nop 0
	v_pk_fma_f32 v[56:57], v[238:239], v[2:3], v[246:247]
	v_lshlrev_b32_e32 v2, 16, v19
	v_and_b32_e32 v3, 0xffff0000, v19
	v_pk_add_f32 v[2:3], v[2:3], v[68:69] op_sel_hi:[1,0] neg_lo:[0,1] neg_hi:[0,1]
	s_nop 0
	v_pk_mul_f32 v[2:3], v[68:69], v[2:3] op_sel:[1,0]
	s_nop 0
	v_pk_fma_f32 v[58:59], v[240:241], v[2:3], v[248:249]
	s_cbranch_vccnz .LBB0_1375
	s_load_dwordx2 s[24:25], s[0:1], 0xb8
	s_waitcnt lgkmcnt(0)
	v_lshl_add_u64 v[2:3], s[24:25], 0, v[138:139]
	v_lshl_add_u64 v[2:3], v[2:3], 0, s[26:27]
	v_add_co_u32_e32 v2, vcc, 0x307b8000, v2
	s_nop 1
	v_addc_co_u32_e32 v3, vcc, 0, v3, vcc
	global_store_dwordx4 v[2:3], v[52:55], off
	global_store_dwordx4 v[2:3], v[56:59], off offset:16
